# qk_post_token: loop-invariant gain loads hoisted out of token loop (fresh VGPRs), removed in-loop vmcnt waits that also drained stores
# speedup vs baseline: 1.0188x; 1.0099x over previous
; DI float bflo(unsigned w) { return __uint_as_float(w << 16); }
; DI float bfhi(unsigned w) { return __uint_as_float(w & 0xffff0000u); }
; DI float shx(float v, int o, int lane) { return __int_as_float(__builtin_amdgcn_ds_bpermute((lane ^ o) << 2, __float_as_int(v))); }
; DI void qk_post_token(bf16_t* prow, const float* rope_t, const float* g_qa, const float* g_ka, const float* g_qb, const float* g_kb, int lane) {
;     const int c = lane & 7, vsub = lane >> 3;
;     u32x4 w[4];
; #pragma unroll
;     for (int L = 0; L < 4; ++L) { const int vid = 8 * L + vsub; const int col = vid * 64 + (vid >= 9 ? 64 : 0) + 8 * c;
;         w[L] = (vid < 30) ? __builtin_nontemporal_load((const u32x4*)(prow + col)) : (u32x4){0u, 0u, 0u, 0u}; }
;     float cs[8], sn[8];
; #pragma unroll
;     for (int q = 0; q < 4; ++q) { const f32x4 t = *(const f32x4*)(rope_t + 16 * (c & 3) + 4 * q); cs[2 * q] = t.x; sn[2 * q] = t.y; cs[2 * q + 1] = t.z; sn[2 * q + 1] = t.w; }
;     const float sgn = c < 4 ? -1.f : 1.f;
; #pragma unroll
;     for (int L = 0; L < 4; ++L) {
;         const int vid = 8 * L + vsub;
;         const int ty = vid < 8 ? 0 : vid == 8 ? 1 : vid < 14 ? 4 : vid < 22 ? 2 : 3;
;         float x[8] = {bflo(w[L].x), bfhi(w[L].x), bflo(w[L].y), bfhi(w[L].y), bflo(w[L].z), bfhi(w[L].z), bflo(w[L].w), bfhi(w[L].w)};
;         float ss = 0.f;
; #pragma unroll
;         for (int e = 0; e < 8; ++e) ss += x[e] * x[e];
;         ss += shx(ss, 1, lane); ss += shx(ss, 2, lane); ss += shx(ss, 4, lane);
;         const float* gp = ty == 0 ? g_qa : ty == 1 ? g_ka : ty == 2 ? g_qb : g_kb;
;         const float rstd = ty < 4 ? 1.0f / sqrtf(ss * (1.f / 64.f) + EPS) : 1.f;
;         const float sc = (ty == 0 || ty == 2) ? QSCALE : 1.f;
;         const f32x4 ga = *(const f32x4*)(gp + 8 * c), gb = *(const f32x4*)(gp + 8 * c + 4);
;         const float gg[8] = {ga.x, ga.y, ga.z, ga.w, gb.x, gb.y, gb.z, gb.w};
.LBB0_345:
	s_or_b64 exec, exec, s[0:1]
	v_readlane_b32 s0, v253, 46
	v_readlane_b32 s1, v253, 47
	s_mov_b32 s1, s75
	v_writelane_b32 v253, s0, 46
	s_mov_b32 s2, s73
	s_waitcnt lgkmcnt(0)
	v_writelane_b32 v253, s1, 47
	s_mov_b64 s[0:1], s[66:67]
	s_barrier
	s_add_i32 s24, s2, s68
	s_cmpk_gt_i32 s24, 0x7fff
	v_mbcnt_lo_u32_b32 v0, -1, 0
	v_mbcnt_hi_u32_b32 v0, -1, v0
	s_cbranch_scc1 .LBB0_372
	s_load_dwordx8 s[4:11], s[0:1], 0x20
	s_load_dwordx2 s[2:3], s[0:1], 0xc8
	v_readlane_b32 s0, v253, 46
	v_readlane_b32 s1, v253, 47
	s_lshl_b32 s74, s0, 6
	s_lshl_b64 s[0:1], s[74:75], 2
	s_waitcnt lgkmcnt(0)
	s_add_u32 s16, s4, s0
	s_addc_u32 s17, s5, s1
	s_add_u32 s20, s6, s0
	s_addc_u32 s21, s7, s1
	s_add_u32 s22, s8, s0
	s_addc_u32 s18, s9, s1
	v_lshlrev_b32_e32 v2, 6, v0
	s_add_u32 s23, s10, s0
	v_ashrrev_i32_e32 v5, 3, v0
	v_and_b32_e32 v2, 0xc0, v2
	v_mov_b32_e32 v3, v98
	s_addc_u32 s19, s11, s1
	v_add_u32_e32 v1, 8, v5
	v_lshl_add_u64 v[2:3], s[2:3], 0, v[2:3]
	s_mov_b64 s[0:1], 0x100000
	v_cmp_lt_i32_e32 vcc, 8, v5
	v_add_u32_e32 v10, 16, v5
	v_lshl_add_u64 v[32:33], v[2:3], 0, s[0:1]
	v_cmp_gt_u32_e64 s[0:1], 22, v1
	v_cndmask_b32_e64 v7, 0, 64, vcc
	v_cmp_lt_i32_e32 vcc, 0, v5
	v_cndmask_b32_e64 v3, 3, 2, s[0:1]
	v_cmp_lt_u32_e64 s[0:1], 13, v1
	v_cmp_gt_u32_e64 s[4:5], 22, v10
	v_and_b32_e32 v4, 7, v0
	v_cndmask_b32_e64 v9, 0, 64, vcc
	v_cmp_lt_i32_e32 vcc, -8, v5
	v_lshlrev_b32_e32 v2, 2, v0
	v_cndmask_b32_e64 v1, 4, v3, s[0:1]
	v_cmp_lt_u32_e64 s[0:1], 7, v0
	v_cndmask_b32_e64 v0, 3, 2, s[4:5]
	v_cmp_lt_u32_e64 s[4:5], 13, v10
	v_cndmask_b32_e64 v11, 0, 64, vcc
	v_add_u32_e32 v12, 24, v5
	v_cmp_lt_i32_e32 vcc, -16, v5
	v_cndmask_b32_e64 v0, 4, v0, s[4:5]
	v_cmp_ne_u32_e64 s[4:5], 8, v10
	v_cndmask_b32_e64 v13, 0, 64, vcc
	v_cmp_gt_u32_e32 vcc, 22, v5
	v_cndmask_b32_e64 v10, 1, v0, s[4:5]
	v_cmp_gt_u32_e64 s[4:5], 22, v12
	v_xor_b32_e32 v70, 4, v2
	v_xor_b32_e32 v71, 8, v2
	v_xor_b32_e32 v72, 16, v2
	v_cndmask_b32_e64 v2, 3, 2, vcc
	v_cmp_lt_u32_e32 vcc, 13, v5
	v_cndmask_b32_e64 v0, 3, 2, s[4:5]
	v_cmp_lt_u32_e64 s[4:5], 13, v12
	v_cndmask_b32_e32 v2, 4, v2, vcc
	v_cmp_eq_u32_e32 vcc, 8, v5
	v_cndmask_b32_e64 v0, 4, v0, s[4:5]
	v_cmp_ne_u32_e64 s[4:5], 8, v12
	v_cndmask_b32_e64 v2, v2, 1, vcc
	v_mov_b32_e32 v15, s19
	v_cndmask_b32_e64 v12, 1, v0, s[4:5]
	v_cmp_gt_i32_e64 s[4:5], 8, v5
	v_mov_b32_e32 v16, s18
	v_mov_b32_e32 v17, s23
	v_cndmask_b32_e64 v2, v2, 0, s[4:5]
	v_cmp_eq_u32_e64 s[18:19], 2, v2
	v_mov_b32_e32 v18, s22
	v_cndmask_b32_e64 v14, 1, v1, s[0:1]
	v_cndmask_b32_e64 v0, v15, v16, s[18:19]
	v_cndmask_b32_e64 v1, v17, v18, s[18:19]
	v_mov_b32_e32 v19, s20
	v_mov_b32_e32 v20, s21
	v_cndmask_b32_e32 v3, v1, v19, vcc
	v_cndmask_b32_e32 v0, v0, v20, vcc
	s_or_b64 vcc, s[4:5], s[18:19]
	v_mov_b32_e32 v23, 0x3e38aa3b
	v_cndmask_b32_e32 v73, 1.0, v23, vcc
	v_cmp_gt_i32_e32 vcc, 0, v5
	v_lshlrev_b32_e32 v6, 3, v4
	v_cmp_gt_u32_e64 s[14:15], 4, v4
	v_mov_b32_e32 v21, s17
	v_mov_b32_e32 v22, s16
	v_cmp_gt_u32_e64 s[16:17], 4, v2
	v_lshlrev_b32_e32 v2, 5, v4
	v_cndmask_b32_e64 v4, v14, 0, vcc
	v_cndmask_b32_e64 v1, v0, v21, s[4:5]
	v_cndmask_b32_e64 v0, v3, v22, s[4:5]
	v_mov_b32_e32 v3, v98
	v_cmp_eq_u32_e64 s[4:5], 2, v4
	v_lshl_add_u64 v[34:35], v[0:1], 0, v[2:3]
	s_or_b64 s[0:1], vcc, s[0:1]
	v_cndmask_b32_e64 v0, v15, v16, s[4:5]
	v_cndmask_b32_e64 v1, v17, v18, s[4:5]
	v_cndmask_b32_e64 v14, v19, v1, s[0:1]
	v_cndmask_b32_e64 v0, v20, v0, s[0:1]
	v_cndmask_b32_e32 v1, v0, v21, vcc
	v_cndmask_b32_e32 v0, v14, v22, vcc
	s_or_b64 vcc, vcc, s[4:5]
	v_cndmask_b32_e32 v74, 1.0, v23, vcc
	v_cmp_gt_i32_e32 vcc, -8, v5
	v_cmp_gt_u32_e64 s[18:19], 4, v4
	v_lshl_add_u64 v[36:37], v[0:1], 0, v[2:3]
	v_cndmask_b32_e64 v4, v10, 0, vcc
	v_cmp_eq_u32_e64 s[0:1], 2, v4
	v_cmp_eq_u32_e64 s[4:5], -8, v5
	v_cmp_gt_u32_e64 s[20:21], 4, v4
	v_cndmask_b32_e64 v0, v15, v16, s[0:1]
	v_cndmask_b32_e64 v1, v17, v18, s[0:1]
	v_cndmask_b32_e64 v10, v1, v19, s[4:5]
	v_cndmask_b32_e64 v0, v0, v20, s[4:5]
	v_cndmask_b32_e32 v1, v0, v21, vcc
	v_cndmask_b32_e32 v0, v10, v22, vcc
	s_or_b64 vcc, vcc, s[0:1]
	v_cndmask_b32_e32 v75, 1.0, v23, vcc
	v_cmp_gt_i32_e32 vcc, -16, v5
	v_lshl_add_u64 v[38:39], v[0:1], 0, v[2:3]
	v_cmp_eq_u32_e64 s[4:5], -16, v5
	v_cndmask_b32_e64 v4, v12, 0, vcc
	v_cmp_eq_u32_e64 s[0:1], 2, v4
	v_cmp_gt_i32_e64 s[6:7], 30, v5
	v_lshlrev_b32_e32 v8, 6, v5
	v_cndmask_b32_e64 v0, v15, v16, s[0:1]
	v_cndmask_b32_e64 v1, v17, v18, s[0:1]
	v_cmp_gt_i32_e64 s[8:9], 22, v5
	v_cmp_gt_i32_e64 s[10:11], 14, v5
	v_cmp_gt_i32_e64 s[12:13], 6, v5
	v_cndmask_b32_e64 v5, v1, v19, s[4:5]
	v_cndmask_b32_e64 v0, v0, v20, s[4:5]
	v_cndmask_b32_e32 v1, v0, v21, vcc
	v_cndmask_b32_e32 v0, v5, v22, vcc
	v_lshl_add_u64 v[40:41], v[0:1], 0, v[2:3]
	v_add_u32_e32 v0, v7, v8
	v_or_b32_e32 v0, v0, v6
	v_ashrrev_i32_e32 v1, 31, v0
	v_lshlrev_b64 v[42:43], 1, v[0:1]
	v_add_u32_e32 v0, v9, v8
	v_or_b32_e32 v0, v0, v6
	v_add_u32_e32 v0, 0x200, v0
	v_ashrrev_i32_e32 v1, 31, v0
	v_lshlrev_b64 v[44:45], 1, v[0:1]
	v_add_u32_e32 v0, v11, v8
	v_or_b32_e32 v0, v0, v6
	v_add_u32_e32 v0, 0x400, v0
	v_ashrrev_i32_e32 v1, 31, v0
	s_or_b64 vcc, vcc, s[0:1]
	s_mul_i32 s1, s24, 0x2400
	v_lshlrev_b64 v[46:47], 1, v[0:1]
	v_add_u32_e32 v0, v13, v8
	s_mul_hi_i32 s0, s24, 0x2400
	s_add_u32 s1, s2, s1
	v_or_b32_e32 v0, v0, v6
	s_addc_u32 s0, s3, s0
	v_add_u32_e32 v0, 0x600, v0
	s_add_u32 s2, s1, 0x9200000
	v_ashrrev_i32_e32 v1, 31, v0
	v_cmp_gt_u32_e64 s[22:23], 4, v4
	v_cndmask_b32_e32 v76, 1.0, v23, vcc
	s_addc_u32 s3, s0, 0
	v_lshlrev_b64 v[48:49], 1, v[0:1]
	global_load_dwordx4 v[144:147], v[34:35], off
	global_load_dwordx4 v[148:151], v[34:35], off offset:16
	global_load_dwordx4 v[152:155], v[36:37], off
	global_load_dwordx4 v[156:159], v[36:37], off offset:16
	global_load_dwordx4 v[160:163], v[38:39], off
	global_load_dwordx4 v[164:167], v[38:39], off offset:16
	global_load_dwordx4 v[168:171], v[40:41], off
	global_load_dwordx4 v[172:175], v[40:41], off offset:16
	s_waitcnt vmcnt(0)
	s_branch .LBB0_348

; DI unsigned pk2(float a, float b) { f32x2 v = {a, b}; bf16x2_t r = __builtin_convertvector(v, bf16x2_t); return __builtin_bit_cast(unsigned, r); }
; DI float bflo(unsigned w) { return __uint_as_float(w << 16); }
; DI float bfhi(unsigned w) { return __uint_as_float(w & 0xffff0000u); }
; DI float shx(float v, int o, int lane) { return __int_as_float(__builtin_amdgcn_ds_bpermute((lane ^ o) << 2, __float_as_int(v))); }
; DI void qk_post_token(bf16_t* prow, const float* rope_t, const float* g_qa, const float* g_ka, const float* g_qb, const float* g_kb, int lane) {
;     ...
;         float x[8] = {bflo(w[L].x), bfhi(w[L].x), bflo(w[L].y), bfhi(w[L].y), bflo(w[L].z), bfhi(w[L].z), bflo(w[L].w), bfhi(w[L].w)};
;         float ss = 0.f;
; #pragma unroll
;         for (int e = 0; e < 8; ++e) ss += x[e] * x[e];
;         ss += shx(ss, 1, lane); ss += shx(ss, 2, lane); ss += shx(ss, 4, lane);
;         const float* gp = ty == 0 ? g_qa : ty == 1 ? g_ka : ty == 2 ? g_qb : g_kb;
;         const float rstd = ty < 4 ? 1.0f / sqrtf(ss * (1.f / 64.f) + EPS) : 1.f;
;         const float sc = (ty == 0 || ty == 2) ? QSCALE : 1.f;
;         const f32x4 ga = *(const f32x4*)(gp + 8 * c), gb = *(const f32x4*)(gp + 8 * c + 4);
;         const float gg[8] = {ga.x, ga.y, ga.z, ga.w, gb.x, gb.y, gb.z, gb.w};
;         float y[8];
; #pragma unroll
;         for (int e = 0; e < 8; ++e) { x[e] = ty < 4 ? x[e] * rstd * gg[e] : x[e]; }
; #pragma unroll
;         for (int e = 0; e < 8; ++e) { const float p = shx(x[e], 4, lane); y[e] = (x[e] * cs[e] + sgn * p * sn[e]) * sc; }
;         u32x4 o; o.x = pk2(y[0], y[1]); o.y = pk2(y[2], y[3]); o.z = pk2(y[4], y[5]); o.w = pk2(y[6], y[7]);
;         const int col = vid * 64 + (vid >= 9 ? 64 : 0) + 8 * c;
;         if (vid < 30) *(u32x4*)(prow + col) = o;
.LBB0_358:
	s_or_b64 exec, exec, s[4:5]
	s_waitcnt lgkmcnt(0)
	v_mul_f32_e32 v63, v62, v58
	v_mul_f32_e32 v68, v62, v28
	v_mul_f32_e32 v69, v62, v59
	v_mul_f32_e32 v77, v62, v29
	v_mul_f32_e32 v82, v62, v60
	v_mul_f32_e32 v83, v62, v30
	v_mul_f32_e32 v84, v62, v61
	v_mul_f32_e32 v62, v62, v31
	s_waitcnt vmcnt(0)
	v_mul_f32_e32 v63, v63, v144
	v_mul_f32_e32 v64, v68, v145
	v_mul_f32_e32 v65, v69, v146
	v_mul_f32_e32 v67, v77, v147
	v_mul_f32_e32 v69, v82, v148
	v_mul_f32_e32 v77, v83, v149
	v_mul_f32_e32 v78, v84, v150
	v_mul_f32_e32 v79, v62, v151
	v_cndmask_b32_e64 v68, v58, v63, s[16:17]
	v_cndmask_b32_e64 v66, v28, v64, s[16:17]
	v_cndmask_b32_e64 v64, v59, v65, s[16:17]
	v_cndmask_b32_e64 v62, v29, v67, s[16:17]
	v_cndmask_b32_e64 v60, v60, v69, s[16:17]
	v_cndmask_b32_e64 v58, v30, v77, s[16:17]
	v_cndmask_b32_e64 v30, v61, v78, s[16:17]
	v_cndmask_b32_e64 v28, v31, v79, s[16:17]
	ds_bpermute_b32 v69, v72, v68
	ds_bpermute_b32 v67, v72, v66
	ds_bpermute_b32 v65, v72, v64
	ds_bpermute_b32 v63, v72, v62
	ds_bpermute_b32 v61, v72, v60
	ds_bpermute_b32 v59, v72, v58
	ds_bpermute_b32 v31, v72, v30
	ds_bpermute_b32 v29, v72, v28
	s_and_saveexec_b64 s[0:1], s[6:7]
	s_cbranch_execz .LBB0_360
	s_waitcnt lgkmcnt(7)
	v_cndmask_b32_e64 v69, v69, -v69, s[14:15]
	s_waitcnt lgkmcnt(6)
	v_cndmask_b32_e64 v67, v67, -v67, s[14:15]
	s_waitcnt lgkmcnt(5)
	v_cndmask_b32_e64 v65, v65, -v65, s[14:15]
	s_waitcnt lgkmcnt(4)
	v_cndmask_b32_e64 v63, v63, -v63, s[14:15]
	s_waitcnt lgkmcnt(3)
	v_cndmask_b32_e64 v61, v61, -v61, s[14:15]
	s_waitcnt lgkmcnt(2)
	v_cndmask_b32_e64 v59, v59, -v59, s[14:15]
	s_waitcnt lgkmcnt(1)
	v_cndmask_b32_e64 v31, v31, -v31, s[14:15]
	s_waitcnt lgkmcnt(0)
	v_cndmask_b32_e64 v29, v29, -v29, s[14:15]
	v_pk_mul_f32 v[68:69], v[12:13], v[68:69]
	v_pk_mul_f32 v[66:67], v[14:15], v[66:67]
	v_pk_mul_f32 v[64:65], v[8:9], v[64:65]
	v_pk_mul_f32 v[62:63], v[10:11], v[62:63]
	v_pk_mul_f32 v[60:61], v[4:5], v[60:61]
	v_pk_mul_f32 v[58:59], v[6:7], v[58:59]
	v_pk_mul_f32 v[30:31], v[0:1], v[30:31]
	v_pk_mul_f32 v[28:29], v[2:3], v[28:29]
	v_add_f32_e32 v68, v68, v69
	v_add_f32_e32 v66, v66, v67
	v_add_f32_e32 v64, v64, v65
	v_add_f32_e32 v62, v62, v63
	v_add_f32_e32 v60, v60, v61
	v_add_f32_e32 v58, v58, v59
	v_add_f32_e32 v30, v30, v31
	v_add_f32_e32 v28, v28, v29
	v_mul_f32_e32 v68, v73, v68
	v_mul_f32_e32 v66, v73, v66
	v_mul_f32_e32 v64, v73, v64
	v_mul_f32_e32 v62, v73, v62
	v_mul_f32_e32 v60, v73, v60
	v_mul_f32_e32 v58, v73, v58
	v_mul_f32_e32 v31, v73, v30
	v_mul_f32_e32 v59, v73, v28
	v_cvt_pk_bf16_f32 v28, v68, v66
	v_cvt_pk_bf16_f32 v29, v64, v62
	v_cvt_pk_bf16_f32 v30, v60, v58
	v_cvt_pk_bf16_f32 v31, v31, v59
	global_store_dwordx4 v[56:57], v[28:31], off

; DI unsigned pk2(float a, float b) { f32x2 v = {a, b}; bf16x2_t r = __builtin_convertvector(v, bf16x2_t); return __builtin_bit_cast(unsigned, r); }
; DI float bflo(unsigned w) { return __uint_as_float(w << 16); }
; DI float bfhi(unsigned w) { return __uint_as_float(w & 0xffff0000u); }
; DI float shx(float v, int o, int lane) { return __int_as_float(__builtin_amdgcn_ds_bpermute((lane ^ o) << 2, __float_as_int(v))); }
; DI void qk_post_token(bf16_t* prow, const float* rope_t, const float* g_qa, const float* g_ka, const float* g_qb, const float* g_kb, int lane) {
;     ...
;         float x[8] = {bflo(w[L].x), bfhi(w[L].x), bflo(w[L].y), bfhi(w[L].y), bflo(w[L].z), bfhi(w[L].z), bflo(w[L].w), bfhi(w[L].w)};
;         float ss = 0.f;
; #pragma unroll
;         for (int e = 0; e < 8; ++e) ss += x[e] * x[e];
;         ss += shx(ss, 1, lane); ss += shx(ss, 2, lane); ss += shx(ss, 4, lane);
;         const float* gp = ty == 0 ? g_qa : ty == 1 ? g_ka : ty == 2 ? g_qb : g_kb;
;         const float rstd = ty < 4 ? 1.0f / sqrtf(ss * (1.f / 64.f) + EPS) : 1.f;
;         const float sc = (ty == 0 || ty == 2) ? QSCALE : 1.f;
;         const f32x4 ga = *(const f32x4*)(gp + 8 * c), gb = *(const f32x4*)(gp + 8 * c + 4);
;         const float gg[8] = {ga.x, ga.y, ga.z, ga.w, gb.x, gb.y, gb.z, gb.w};
;         float y[8];
; #pragma unroll
;         for (int e = 0; e < 8; ++e) { x[e] = ty < 4 ? x[e] * rstd * gg[e] : x[e]; }
; #pragma unroll
;         for (int e = 0; e < 8; ++e) { const float p = shx(x[e], 4, lane); y[e] = (x[e] * cs[e] + sgn * p * sn[e]) * sc; }
;         u32x4 o; o.x = pk2(y[0], y[1]); o.y = pk2(y[2], y[3]); o.z = pk2(y[4], y[5]); o.w = pk2(y[6], y[7]);
;         const int col = vid * 64 + (vid >= 9 ? 64 : 0) + 8 * c;
;         if (vid < 30) *(u32x4*)(prow + col) = o;
.LBB0_362:
	s_or_b64 exec, exec, s[4:5]
	s_waitcnt lgkmcnt(0)
	v_mul_f32_e32 v57, v56, v28
	v_mul_f32_e32 v66, v56, v24
	v_mul_f32_e32 v67, v56, v29
	v_mul_f32_e32 v68, v56, v25
	v_mul_f32_e32 v69, v56, v30
	v_mul_f32_e32 v77, v56, v26
	v_mul_f32_e32 v78, v56, v31
	v_mul_f32_e32 v56, v56, v27
	v_mul_f32_e32 v57, v57, v152
	v_mul_f32_e32 v58, v66, v153
	v_mul_f32_e32 v59, v67, v154
	v_mul_f32_e32 v61, v68, v155
	v_mul_f32_e32 v66, v69, v156
	v_mul_f32_e32 v63, v77, v157
	v_mul_f32_e32 v64, v78, v158
	v_mul_f32_e32 v65, v56, v159
	v_cndmask_b32_e64 v62, v28, v57, s[18:19]
	v_cndmask_b32_e64 v60, v24, v58, s[18:19]
	v_cndmask_b32_e64 v58, v29, v59, s[18:19]
	v_cndmask_b32_e64 v56, v25, v61, s[18:19]
	v_cndmask_b32_e64 v30, v30, v66, s[18:19]
	v_cndmask_b32_e64 v28, v26, v63, s[18:19]
	v_cndmask_b32_e64 v26, v31, v64, s[18:19]
	v_cndmask_b32_e64 v24, v27, v65, s[18:19]
	ds_bpermute_b32 v63, v72, v62
	ds_bpermute_b32 v61, v72, v60
	ds_bpermute_b32 v59, v72, v58
	ds_bpermute_b32 v57, v72, v56
	ds_bpermute_b32 v31, v72, v30
	ds_bpermute_b32 v29, v72, v28
	ds_bpermute_b32 v27, v72, v26
	ds_bpermute_b32 v25, v72, v24
	s_and_saveexec_b64 s[0:1], s[8:9]
	s_cbranch_execz .LBB0_364
	s_waitcnt lgkmcnt(7)
	v_cndmask_b32_e64 v63, v63, -v63, s[14:15]
	s_waitcnt lgkmcnt(6)
	v_cndmask_b32_e64 v61, v61, -v61, s[14:15]
	s_waitcnt lgkmcnt(5)
	v_cndmask_b32_e64 v59, v59, -v59, s[14:15]
	s_waitcnt lgkmcnt(4)
	v_cndmask_b32_e64 v57, v57, -v57, s[14:15]
	s_waitcnt lgkmcnt(3)
	v_cndmask_b32_e64 v31, v31, -v31, s[14:15]
	s_waitcnt lgkmcnt(2)
	v_cndmask_b32_e64 v29, v29, -v29, s[14:15]
	s_waitcnt lgkmcnt(1)
	v_cndmask_b32_e64 v27, v27, -v27, s[14:15]
	s_waitcnt lgkmcnt(0)
	v_cndmask_b32_e64 v25, v25, -v25, s[14:15]
	v_pk_mul_f32 v[62:63], v[12:13], v[62:63]
	v_pk_mul_f32 v[60:61], v[14:15], v[60:61]
	v_pk_mul_f32 v[58:59], v[8:9], v[58:59]
	v_pk_mul_f32 v[56:57], v[10:11], v[56:57]
	v_pk_mul_f32 v[30:31], v[4:5], v[30:31]
	v_pk_mul_f32 v[28:29], v[6:7], v[28:29]
	v_pk_mul_f32 v[26:27], v[0:1], v[26:27]
	v_pk_mul_f32 v[24:25], v[2:3], v[24:25]
	v_add_f32_e32 v62, v62, v63
	v_add_f32_e32 v60, v60, v61
	v_add_f32_e32 v58, v58, v59
	v_add_f32_e32 v56, v56, v57
	v_add_f32_e32 v30, v30, v31
	v_add_f32_e32 v28, v28, v29
	v_add_f32_e32 v26, v26, v27
	v_add_f32_e32 v24, v24, v25
	v_mul_f32_e32 v62, v74, v62
	v_mul_f32_e32 v60, v74, v60
	v_mul_f32_e32 v58, v74, v58
	v_mul_f32_e32 v56, v74, v56
	v_mul_f32_e32 v30, v74, v30
	v_mul_f32_e32 v28, v74, v28
	v_mul_f32_e32 v27, v74, v26
	v_mul_f32_e32 v29, v74, v24
	v_cvt_pk_bf16_f32 v24, v62, v60
	v_cvt_pk_bf16_f32 v25, v58, v56
	v_cvt_pk_bf16_f32 v26, v30, v28
	v_cvt_pk_bf16_f32 v27, v27, v29
	global_store_dwordx4 v[54:55], v[24:27], off

; DI unsigned pk2(float a, float b) { f32x2 v = {a, b}; bf16x2_t r = __builtin_convertvector(v, bf16x2_t); return __builtin_bit_cast(unsigned, r); }
; DI float bflo(unsigned w) { return __uint_as_float(w << 16); }
; DI float bfhi(unsigned w) { return __uint_as_float(w & 0xffff0000u); }
; DI float shx(float v, int o, int lane) { return __int_as_float(__builtin_amdgcn_ds_bpermute((lane ^ o) << 2, __float_as_int(v))); }
; DI void qk_post_token(bf16_t* prow, const float* rope_t, const float* g_qa, const float* g_ka, const float* g_qb, const float* g_kb, int lane) {
;     ...
;         float x[8] = {bflo(w[L].x), bfhi(w[L].x), bflo(w[L].y), bfhi(w[L].y), bflo(w[L].z), bfhi(w[L].z), bflo(w[L].w), bfhi(w[L].w)};
;         float ss = 0.f;
; #pragma unroll
;         for (int e = 0; e < 8; ++e) ss += x[e] * x[e];
;         ss += shx(ss, 1, lane); ss += shx(ss, 2, lane); ss += shx(ss, 4, lane);
;         const float* gp = ty == 0 ? g_qa : ty == 1 ? g_ka : ty == 2 ? g_qb : g_kb;
;         const float rstd = ty < 4 ? 1.0f / sqrtf(ss * (1.f / 64.f) + EPS) : 1.f;
;         const float sc = (ty == 0 || ty == 2) ? QSCALE : 1.f;
;         const f32x4 ga = *(const f32x4*)(gp + 8 * c), gb = *(const f32x4*)(gp + 8 * c + 4);
;         const float gg[8] = {ga.x, ga.y, ga.z, ga.w, gb.x, gb.y, gb.z, gb.w};
;         float y[8];
; #pragma unroll
;         for (int e = 0; e < 8; ++e) { x[e] = ty < 4 ? x[e] * rstd * gg[e] : x[e]; }
; #pragma unroll
;         for (int e = 0; e < 8; ++e) { const float p = shx(x[e], 4, lane); y[e] = (x[e] * cs[e] + sgn * p * sn[e]) * sc; }
;         u32x4 o; o.x = pk2(y[0], y[1]); o.y = pk2(y[2], y[3]); o.z = pk2(y[4], y[5]); o.w = pk2(y[6], y[7]);
;         const int col = vid * 64 + (vid >= 9 ? 64 : 0) + 8 * c;
;         if (vid < 30) *(u32x4*)(prow + col) = o;
.LBB0_366:
	s_or_b64 exec, exec, s[4:5]
	v_mul_f32_e32 v28, v23, v24
	s_waitcnt lgkmcnt(0)
	v_mul_f32_e32 v30, v23, v20
	v_mul_f32_e32 v31, v23, v25
	v_mul_f32_e32 v62, v23, v26
	v_mul_f32_e32 v63, v23, v27
	v_mul_f32_e32 v64, v23, v22
	v_mul_f32_e32 v65, v23, v29
	v_mul_f32_e32 v23, v23, v21
	v_mul_f32_e32 v28, v28, v160
	v_mul_f32_e32 v30, v30, v161
	v_mul_f32_e32 v31, v31, v162
	v_mul_f32_e32 v55, v62, v163
	v_mul_f32_e32 v57, v63, v164
	v_mul_f32_e32 v58, v64, v165
	v_mul_f32_e32 v59, v65, v166
	v_mul_f32_e32 v23, v23, v167
	v_cndmask_b32_e64 v56, v24, v28, s[20:21]
	v_cndmask_b32_e64 v54, v20, v30, s[20:21]
	v_cndmask_b32_e64 v30, v25, v31, s[20:21]
	v_cndmask_b32_e64 v28, v26, v55, s[20:21]
	v_cndmask_b32_e64 v24, v27, v57, s[20:21]
	v_cndmask_b32_e64 v22, v22, v58, s[20:21]
	v_cndmask_b32_e64 v20, v29, v59, s[20:21]
	v_cndmask_b32_e64 v26, v21, v23, s[20:21]
	ds_bpermute_b32 v57, v72, v56
	ds_bpermute_b32 v55, v72, v54
	ds_bpermute_b32 v31, v72, v30
	ds_bpermute_b32 v29, v72, v28
	ds_bpermute_b32 v25, v72, v24
	ds_bpermute_b32 v23, v72, v22
	ds_bpermute_b32 v21, v72, v20
	ds_bpermute_b32 v27, v72, v26
	s_and_saveexec_b64 s[0:1], s[10:11]
	s_cbranch_execz .LBB0_368
	s_waitcnt lgkmcnt(1)
	v_cndmask_b32_e64 v21, v21, -v21, s[14:15]
	v_cndmask_b32_e64 v23, v23, -v23, s[14:15]
	v_pk_mul_f32 v[20:21], v[0:1], v[20:21]
	v_cndmask_b32_e64 v57, v57, -v57, s[14:15]
	v_cndmask_b32_e64 v55, v55, -v55, s[14:15]
	v_cndmask_b32_e64 v31, v31, -v31, s[14:15]
	v_cndmask_b32_e64 v29, v29, -v29, s[14:15]
	v_cndmask_b32_e64 v25, v25, -v25, s[14:15]
	v_pk_mul_f32 v[22:23], v[6:7], v[22:23]
	v_add_f32_e32 v20, v20, v21
	s_waitcnt lgkmcnt(0)
	v_cndmask_b32_e64 v27, v27, -v27, s[14:15]
	v_pk_mul_f32 v[56:57], v[12:13], v[56:57]
	v_pk_mul_f32 v[54:55], v[14:15], v[54:55]
	v_pk_mul_f32 v[30:31], v[8:9], v[30:31]
	v_pk_mul_f32 v[28:29], v[10:11], v[28:29]
	v_pk_mul_f32 v[24:25], v[4:5], v[24:25]
	v_add_f32_e32 v22, v22, v23
	v_mul_f32_e32 v23, v75, v20
	v_pk_mul_f32 v[20:21], v[2:3], v[26:27]
	v_add_f32_e32 v56, v56, v57
	v_add_f32_e32 v54, v54, v55
	v_add_f32_e32 v30, v30, v31
	v_add_f32_e32 v28, v28, v29
	v_add_f32_e32 v24, v24, v25
	v_add_f32_e32 v20, v20, v21
	v_mul_f32_e32 v56, v75, v56
	v_mul_f32_e32 v54, v75, v54
	v_mul_f32_e32 v30, v75, v30
	v_mul_f32_e32 v28, v75, v28
	v_mul_f32_e32 v24, v75, v24
	v_mul_f32_e32 v22, v75, v22
	v_mul_f32_e32 v25, v75, v20
	v_cvt_pk_bf16_f32 v20, v56, v54
	v_cvt_pk_bf16_f32 v21, v30, v28
	v_cvt_pk_bf16_f32 v22, v24, v22
	v_cvt_pk_bf16_f32 v23, v23, v25
	global_store_dwordx4 v[52:53], v[20:23], off

; DI unsigned pk2(float a, float b) { f32x2 v = {a, b}; bf16x2_t r = __builtin_convertvector(v, bf16x2_t); return __builtin_bit_cast(unsigned, r); }
; DI float bflo(unsigned w) { return __uint_as_float(w << 16); }
; DI float bfhi(unsigned w) { return __uint_as_float(w & 0xffff0000u); }
; DI float shx(float v, int o, int lane) { return __int_as_float(__builtin_amdgcn_ds_bpermute((lane ^ o) << 2, __float_as_int(v))); }
; DI void qk_post_token(bf16_t* prow, const float* rope_t, const float* g_qa, const float* g_ka, const float* g_qb, const float* g_kb, int lane) {
;     ...
;         float x[8] = {bflo(w[L].x), bfhi(w[L].x), bflo(w[L].y), bfhi(w[L].y), bflo(w[L].z), bfhi(w[L].z), bflo(w[L].w), bfhi(w[L].w)};
;         float ss = 0.f;
; #pragma unroll
;         for (int e = 0; e < 8; ++e) ss += x[e] * x[e];
;         ss += shx(ss, 1, lane); ss += shx(ss, 2, lane); ss += shx(ss, 4, lane);
;         const float* gp = ty == 0 ? g_qa : ty == 1 ? g_ka : ty == 2 ? g_qb : g_kb;
;         const float rstd = ty < 4 ? 1.0f / sqrtf(ss * (1.f / 64.f) + EPS) : 1.f;
;         const float sc = (ty == 0 || ty == 2) ? QSCALE : 1.f;
;         const f32x4 ga = *(const f32x4*)(gp + 8 * c), gb = *(const f32x4*)(gp + 8 * c + 4);
;         const float gg[8] = {ga.x, ga.y, ga.z, ga.w, gb.x, gb.y, gb.z, gb.w};
;         float y[8];
; #pragma unroll
;         for (int e = 0; e < 8; ++e) { x[e] = ty < 4 ? x[e] * rstd * gg[e] : x[e]; }
; #pragma unroll
;         for (int e = 0; e < 8; ++e) { const float p = shx(x[e], 4, lane); y[e] = (x[e] * cs[e] + sgn * p * sn[e]) * sc; }
;         u32x4 o; o.x = pk2(y[0], y[1]); o.y = pk2(y[2], y[3]); o.z = pk2(y[4], y[5]); o.w = pk2(y[6], y[7]);
;         const int col = vid * 64 + (vid >= 9 ? 64 : 0) + 8 * c;
;         if (vid < 30) *(u32x4*)(prow + col) = o;
;     }
; }
.LBB0_370:
	s_or_b64 exec, exec, s[4:5]
	s_waitcnt lgkmcnt(0)
	v_mul_f32_e32 v25, v24, v20
	v_mul_f32_e32 v30, v24, v16
	v_mul_f32_e32 v31, v24, v21
	v_mul_f32_e32 v56, v24, v17
	v_mul_f32_e32 v57, v24, v22
	v_mul_f32_e32 v58, v24, v18
	v_mul_f32_e32 v59, v24, v23
	v_mul_f32_e32 v24, v24, v19
	v_mul_f32_e32 v25, v25, v168
	v_mul_f32_e32 v26, v30, v169
	v_mul_f32_e32 v27, v31, v170
	v_mul_f32_e32 v29, v56, v171
	v_mul_f32_e32 v31, v57, v172
	v_mul_f32_e32 v52, v58, v173
	v_mul_f32_e32 v53, v59, v174
	v_mul_f32_e32 v54, v24, v175
	v_cndmask_b32_e64 v30, v20, v25, s[22:23]
	v_cndmask_b32_e64 v28, v16, v26, s[22:23]
	v_cndmask_b32_e64 v26, v21, v27, s[22:23]
	v_cndmask_b32_e64 v24, v17, v29, s[22:23]
	v_cndmask_b32_e64 v22, v22, v31, s[22:23]
	v_cndmask_b32_e64 v20, v18, v52, s[22:23]
	v_cndmask_b32_e64 v18, v23, v53, s[22:23]
	v_cndmask_b32_e64 v16, v19, v54, s[22:23]
	ds_bpermute_b32 v31, v72, v30
	ds_bpermute_b32 v29, v72, v28
	ds_bpermute_b32 v27, v72, v26
	ds_bpermute_b32 v25, v72, v24
	ds_bpermute_b32 v23, v72, v22
	ds_bpermute_b32 v21, v72, v20
	ds_bpermute_b32 v19, v72, v18
	ds_bpermute_b32 v17, v72, v16
	s_and_saveexec_b64 s[0:1], s[12:13]
	s_cbranch_execz .LBB0_347
	s_waitcnt lgkmcnt(7)
	v_cndmask_b32_e64 v31, v31, -v31, s[14:15]
	v_pk_mul_f32 v[12:13], v[12:13], v[30:31]
	s_waitcnt lgkmcnt(5)
	v_cndmask_b32_e64 v27, v27, -v27, s[14:15]
	v_add_f32_e32 v12, v12, v13
	v_cndmask_b32_e64 v29, v29, -v29, s[14:15]
	v_pk_mul_f32 v[8:9], v[8:9], v[26:27]
	s_waitcnt lgkmcnt(3)
	v_cndmask_b32_e64 v23, v23, -v23, s[14:15]
	v_mul_f32_e32 v30, v76, v12
	v_pk_mul_f32 v[12:13], v[14:15], v[28:29]
	v_add_f32_e32 v8, v8, v9
	v_cndmask_b32_e64 v25, v25, -v25, s[14:15]
	v_pk_mul_f32 v[4:5], v[4:5], v[22:23]
	s_waitcnt lgkmcnt(1)
	v_cndmask_b32_e64 v19, v19, -v19, s[14:15]
	v_add_f32_e32 v12, v12, v13
	v_mul_f32_e32 v13, v76, v8
	v_pk_mul_f32 v[8:9], v[10:11], v[24:25]
	v_add_f32_e32 v4, v4, v5
	v_cndmask_b32_e64 v21, v21, -v21, s[14:15]
	v_pk_mul_f32 v[0:1], v[0:1], v[18:19]
	v_add_f32_e32 v8, v8, v9
	v_mul_f32_e32 v9, v76, v4
	v_pk_mul_f32 v[4:5], v[6:7], v[20:21]
	v_add_f32_e32 v0, v0, v1
	s_waitcnt lgkmcnt(0)
	v_cndmask_b32_e64 v17, v17, -v17, s[14:15]
	v_add_f32_e32 v4, v4, v5
	v_mul_f32_e32 v5, v76, v0
	v_pk_mul_f32 v[0:1], v[2:3], v[16:17]
	v_mul_f32_e32 v12, v76, v12
	v_add_f32_e32 v0, v0, v1
	v_mul_f32_e32 v8, v76, v8
	v_mul_f32_e32 v4, v76, v4
	v_mul_f32_e32 v3, v76, v0
	v_cvt_pk_bf16_f32 v0, v30, v12
	v_cvt_pk_bf16_f32 v1, v13, v8
	v_cvt_pk_bf16_f32 v2, v9, v4
	v_cvt_pk_bf16_f32 v3, v5, v3
	global_store_dwordx4 v[50:51], v[0:3], off
	s_branch .LBB0_347
